# XCD-local seams poll the arrival counter against a per-seam constant target (one hop; no ticket round trip, no generation word)
# speedup vs baseline: 1.0009x; 1.0009x over previous
; __device__ __forceinline__ unsigned xb_ld(unsigned* p)              { return __hip_atomic_load(p, __ATOMIC_RELAXED, __HIP_MEMORY_SCOPE_AGENT); }
; __device__ __forceinline__ unsigned xb_add(unsigned* p, unsigned v) { return __hip_atomic_fetch_add(p, v, __ATOMIC_RELAXED, __HIP_MEMORY_SCOPE_AGENT); }
; __device__ __forceinline__ void xcd_local_barrier(unsigned* xl, unsigned x) {
;     asm volatile("s_waitcnt vmcnt(0)" ::: "memory");
;     __syncthreads();
;     if (threadIdx.x == 0) {
;         __builtin_amdgcn_s_waitcnt(0);
;         unsigned* sub = xl + 512 + 64 * x; unsigned* gen = xl + 1024 + 64 * x;
;         const unsigned old = xb_add(sub, 1u), g = old / 32u;
;         if (old + 1u == (g + 1u) * 32u) (void)xb_add(gen, 1u);
;         else { unsigned sp = 0; while (xb_ld(gen) == g) { __builtin_amdgcn_s_sleep(1); if (++sp > (1u << 22)) break; } }
;         __builtin_amdgcn_fence(__ATOMIC_ACQUIRE, "agent");
;         asm volatile("s_waitcnt vmcnt(0)" ::: "memory");
;     }
;     __syncthreads();
.LBB0_668:
	s_and_b64 vcc, exec, s[4:5]
	s_cbranch_vccz .LBB0_692
	s_waitcnt vmcnt(0)
	s_waitcnt vmcnt(0) lgkmcnt(0)
	s_barrier
	s_and_saveexec_b64 s[2:3], s[90:91]
	s_cbranch_execz .LBB0_691
	s_lshl_b32 s4, s92, 8
	s_add_u32 s4, s74, s4
	s_addc_u32 s5, s75, 0
	v_mov_b32_e32 v0, 0xd000
	v_mov_b32_e32 v1, 1
	s_waitcnt vmcnt(0) lgkmcnt(0)
	global_atomic_add v0, v1, s[4:5]
	s_mov_b32 s23, 0x40000
.Lxs0_spin:
	global_load_dword v2, v0, s[4:5] sc1
	s_waitcnt vmcnt(0)
	v_cmp_gt_u32_e32 vcc, 0x20, v2
	s_cbranch_vccz .Lxs0_done
	s_sleep 1
	s_sub_u32 s23, s23, 1
	s_cmp_lg_u32 s23, 0
	s_cbranch_scc1 .Lxs0_spin
.Lxs0_done:
	buffer_inv sc1
	s_waitcnt vmcnt(0)
.LBB0_691:
	s_or_b64 exec, exec, s[2:3]
	s_barrier

; __device__ __forceinline__ unsigned xb_ld(unsigned* p)              { return __hip_atomic_load(p, __ATOMIC_RELAXED, __HIP_MEMORY_SCOPE_AGENT); }
; __device__ __forceinline__ unsigned xb_add(unsigned* p, unsigned v) { return __hip_atomic_fetch_add(p, v, __ATOMIC_RELAXED, __HIP_MEMORY_SCOPE_AGENT); }
; __device__ __forceinline__ void xcd_local_barrier(unsigned* xl, unsigned x) {
;     asm volatile("s_waitcnt vmcnt(0)" ::: "memory");
;     __syncthreads();
;     if (threadIdx.x == 0) {
;         __builtin_amdgcn_s_waitcnt(0);
;         unsigned* sub = xl + 512 + 64 * x; unsigned* gen = xl + 1024 + 64 * x;
;         const unsigned old = xb_add(sub, 1u), g = old / 32u;
;         if (old + 1u == (g + 1u) * 32u) (void)xb_add(gen, 1u);
;         else { unsigned sp = 0; while (xb_ld(gen) == g) { __builtin_amdgcn_s_sleep(1); if (++sp > (1u << 22)) break; } }
;         __builtin_amdgcn_fence(__ATOMIC_ACQUIRE, "agent");
;         asm volatile("s_waitcnt vmcnt(0)" ::: "memory");
;     }
;     __syncthreads();
.LBB0_793:
	s_and_b64 vcc, exec, s[2:3]
	s_cbranch_vccz .LBB0_817
	s_waitcnt vmcnt(0)
	s_waitcnt vmcnt(0) lgkmcnt(0)
	s_barrier
	s_and_saveexec_b64 s[2:3], s[90:91]
	s_cbranch_execz .LBB0_816
	s_lshl_b32 s4, s92, 8
	s_add_u32 s4, s74, s4
	s_addc_u32 s5, s75, 0
	v_mov_b32_e32 v0, 0xd000
	v_mov_b32_e32 v1, 1
	s_waitcnt vmcnt(0) lgkmcnt(0)
	global_atomic_add v0, v1, s[4:5]
	s_mov_b32 s23, 0x40000
.Lxs1_spin:
	global_load_dword v2, v0, s[4:5] sc1
	s_waitcnt vmcnt(0)
	v_cmp_gt_u32_e32 vcc, 0x40, v2
	s_cbranch_vccz .Lxs1_done
	s_sleep 1
	s_sub_u32 s23, s23, 1
	s_cmp_lg_u32 s23, 0
	s_cbranch_scc1 .Lxs1_spin
.Lxs1_done:
	buffer_inv sc1
	s_waitcnt vmcnt(0)
.LBB0_816:
	s_or_b64 exec, exec, s[2:3]
	s_barrier

; __device__ __forceinline__ unsigned xb_ld(unsigned* p)              { return __hip_atomic_load(p, __ATOMIC_RELAXED, __HIP_MEMORY_SCOPE_AGENT); }
; __device__ __forceinline__ unsigned xb_add(unsigned* p, unsigned v) { return __hip_atomic_fetch_add(p, v, __ATOMIC_RELAXED, __HIP_MEMORY_SCOPE_AGENT); }
; __device__ __forceinline__ void xcd_local_barrier(unsigned* xl, unsigned x) {
;     asm volatile("s_waitcnt vmcnt(0)" ::: "memory");
;     __syncthreads();
;     if (threadIdx.x == 0) {
;         __builtin_amdgcn_s_waitcnt(0);
;         unsigned* sub = xl + 512 + 64 * x; unsigned* gen = xl + 1024 + 64 * x;
;         const unsigned old = xb_add(sub, 1u), g = old / 32u;
;         if (old + 1u == (g + 1u) * 32u) (void)xb_add(gen, 1u);
;         else { unsigned sp = 0; while (xb_ld(gen) == g) { __builtin_amdgcn_s_sleep(1); if (++sp > (1u << 22)) break; } }
;         __builtin_amdgcn_fence(__ATOMIC_ACQUIRE, "agent");
;         asm volatile("s_waitcnt vmcnt(0)" ::: "memory");
;     }
;     __syncthreads();
.Lxs2_spin:
	global_load_dword v2, v0, s[4:5] sc1
	s_waitcnt vmcnt(0)
	v_cmp_gt_u32_e32 vcc, 0x60, v2
	s_cbranch_vccz .Lxs2_done
	s_sleep 1
	s_sub_u32 s23, s23, 1
	s_cmp_lg_u32 s23, 0
	s_cbranch_scc1 .Lxs2_spin
.Lxs2_done:
	buffer_inv sc1
	s_waitcnt vmcnt(0)
.LBB0_1038:
	s_or_b64 exec, exec, s[2:3]
	s_barrier

; __device__ __forceinline__ unsigned xb_add(unsigned* p, unsigned v) { return __hip_atomic_fetch_add(p, v, __ATOMIC_RELAXED, __HIP_MEMORY_SCOPE_AGENT); }
; __device__ __forceinline__ void xcd_local_barrier(unsigned* xl, unsigned x) {
;     asm volatile("s_waitcnt vmcnt(0)" ::: "memory");
;     __syncthreads();
;     if (threadIdx.x == 0) {
;         __builtin_amdgcn_s_waitcnt(0);
;         unsigned* sub = xl + 512 + 64 * x; unsigned* gen = xl + 1024 + 64 * x;
;         const unsigned old = xb_add(sub, 1u), g = old / 32u;
;         if (old + 1u == (g + 1u) * 32u) (void)xb_add(gen, 1u);
; __global__ void __launch_bounds__(NWAVES * 64, 2) fwd_megakernel(Args args) {
;     ...
;             if (myrank < 24) { const int b = 2 * myx + myrank / 12, rem = myrank % 12; mlstm_state_group(args, lds, b * 4 + rem / 3, rem % 3, tid, wave, lane); }
;             for (int k = 0; k < 4; ++k) { const int l = myrank + 32 * k; attn_item(args, lds, ((2 * myx + (l >> 6)) << 6) | (l & 63), tid, wave, lane); }
.LBB0_1086:
	s_waitcnt vmcnt(0) lgkmcnt(0)
	s_barrier
	s_and_saveexec_b64 s[4:5], s[90:91]
	s_cbranch_execz .Lsp_post_end
	s_lshl_b32 s6, s92, 8
	s_add_u32 s6, s74, s6
	s_addc_u32 s7, s75, 0
	v_mov_b32_e32 v246, 0xd000
	v_mov_b32_e32 v247, 1
	global_atomic_add v246, v247, s[6:7]

; __device__ __forceinline__ unsigned xb_ld(unsigned* p)              { return __hip_atomic_load(p, __ATOMIC_RELAXED, __HIP_MEMORY_SCOPE_AGENT); }
; __device__ __forceinline__ unsigned xb_add(unsigned* p, unsigned v) { return __hip_atomic_fetch_add(p, v, __ATOMIC_RELAXED, __HIP_MEMORY_SCOPE_AGENT); }
; __device__ __forceinline__ void xcd_local_barrier(unsigned* xl, unsigned x) {
;     asm volatile("s_waitcnt vmcnt(0)" ::: "memory");
;     __syncthreads();
;     if (threadIdx.x == 0) {
;         __builtin_amdgcn_s_waitcnt(0);
;         unsigned* sub = xl + 512 + 64 * x; unsigned* gen = xl + 1024 + 64 * x;
;         const unsigned old = xb_add(sub, 1u), g = old / 32u;
;         if (old + 1u == (g + 1u) * 32u) (void)xb_add(gen, 1u);
;         else { unsigned sp = 0; while (xb_ld(gen) == g) { __builtin_amdgcn_s_sleep(1); if (++sp > (1u << 22)) break; } }
;         __builtin_amdgcn_fence(__ATOMIC_ACQUIRE, "agent");
;         asm volatile("s_waitcnt vmcnt(0)" ::: "memory");
;     }
;     __syncthreads();
.LBB0_1163:
	s_and_b64 vcc, exec, s[4:5]
	s_cbranch_vccz .LBB0_1187
	s_and_saveexec_b64 s[4:5], s[90:91]
	s_cbranch_execz .Lsp_wait_end
	s_lshl_b32 s6, s92, 8
	s_add_u32 s6, s74, s6
	s_addc_u32 s7, s75, 0
	v_mov_b32_e32 v246, 0xd000
	s_mov_b32 s0, 0x40000
.Lsp_spin:
	global_load_dword v247, v246, s[6:7] sc1
	s_waitcnt vmcnt(0)
	v_cmp_gt_u32_e32 vcc, 0x80, v247
	s_cbranch_vccz .Lsp_spun
	s_sleep 1
	s_sub_u32 s0, s0, 1
	s_cmp_lg_u32 s0, 0
	s_cbranch_scc1 .Lsp_spin

; __device__ __forceinline__ unsigned xb_ld(unsigned* p)              { return __hip_atomic_load(p, __ATOMIC_RELAXED, __HIP_MEMORY_SCOPE_AGENT); }
; __device__ __forceinline__ unsigned xb_add(unsigned* p, unsigned v) { return __hip_atomic_fetch_add(p, v, __ATOMIC_RELAXED, __HIP_MEMORY_SCOPE_AGENT); }
; __device__ __forceinline__ void xcd_local_barrier(unsigned* xl, unsigned x) {
;     asm volatile("s_waitcnt vmcnt(0)" ::: "memory");
;     __syncthreads();
;     if (threadIdx.x == 0) {
;         __builtin_amdgcn_s_waitcnt(0);
;         unsigned* sub = xl + 512 + 64 * x; unsigned* gen = xl + 1024 + 64 * x;
;         const unsigned old = xb_add(sub, 1u), g = old / 32u;
;         if (old + 1u == (g + 1u) * 32u) (void)xb_add(gen, 1u);
;         else { unsigned sp = 0; while (xb_ld(gen) == g) { __builtin_amdgcn_s_sleep(1); if (++sp > (1u << 22)) break; } }
;         __builtin_amdgcn_fence(__ATOMIC_ACQUIRE, "agent");
;         asm volatile("s_waitcnt vmcnt(0)" ::: "memory");
;     }
;     __syncthreads();
.LBB0_1308:
	s_and_b64 vcc, exec, s[2:3]
	s_cbranch_vccz .LBB0_1332
	s_waitcnt vmcnt(0)
	s_barrier
	s_and_saveexec_b64 s[2:3], s[90:91]
	s_cbranch_execz .LBB0_1331
	s_lshl_b32 s4, s92, 8
	s_add_u32 s4, s74, s4
	s_addc_u32 s5, s75, 0
	v_mov_b32_e32 v0, 0xd000
	v_mov_b32_e32 v1, 1
	s_waitcnt vmcnt(0) lgkmcnt(0)
	global_atomic_add v0, v1, s[4:5]
	s_mov_b32 s23, 0x40000
.Lxs3_spin:
	global_load_dword v2, v0, s[4:5] sc1
	s_waitcnt vmcnt(0)
	v_cmp_gt_u32_e32 vcc, 0xa0, v2
	s_cbranch_vccz .Lxs3_done
	s_sleep 1
	s_sub_u32 s23, s23, 1
	s_cmp_lg_u32 s23, 0
	s_cbranch_scc1 .Lxs3_spin
.Lxs3_done:
	buffer_inv sc1
	s_waitcnt vmcnt(0)
.LBB0_1331:
	s_or_b64 exec, exec, s[2:3]
	s_barrier

; __device__ __forceinline__ unsigned xb_ld(unsigned* p)              { return __hip_atomic_load(p, __ATOMIC_RELAXED, __HIP_MEMORY_SCOPE_AGENT); }
; __device__ __forceinline__ unsigned xb_add(unsigned* p, unsigned v) { return __hip_atomic_fetch_add(p, v, __ATOMIC_RELAXED, __HIP_MEMORY_SCOPE_AGENT); }
; __device__ __forceinline__ void xcd_local_barrier(unsigned* xl, unsigned x) {
;     asm volatile("s_waitcnt vmcnt(0)" ::: "memory");
;     __syncthreads();
;     if (threadIdx.x == 0) {
;         __builtin_amdgcn_s_waitcnt(0);
;         unsigned* sub = xl + 512 + 64 * x; unsigned* gen = xl + 1024 + 64 * x;
;         const unsigned old = xb_add(sub, 1u), g = old / 32u;
;         if (old + 1u == (g + 1u) * 32u) (void)xb_add(gen, 1u);
;         else { unsigned sp = 0; while (xb_ld(gen) == g) { __builtin_amdgcn_s_sleep(1); if (++sp > (1u << 22)) break; } }
;         __builtin_amdgcn_fence(__ATOMIC_ACQUIRE, "agent");
;         asm volatile("s_waitcnt vmcnt(0)" ::: "memory");
;     }
;     __syncthreads();
.Lxs4_spin:
	global_load_dword v2, v0, s[4:5] sc1
	s_waitcnt vmcnt(0)
	v_cmp_gt_u32_e32 vcc, 0xc0, v2
	s_cbranch_vccz .Lxs4_done
	s_sleep 1
	s_sub_u32 s23, s23, 1
	s_cmp_lg_u32 s23, 0
	s_cbranch_scc1 .Lxs4_spin
.Lxs4_done:
	buffer_inv sc1
	s_waitcnt vmcnt(0)
.LBB0_1436:
	s_or_b64 exec, exec, s[2:3]
	s_barrier

; __device__ __forceinline__ unsigned xb_ld(unsigned* p)              { return __hip_atomic_load(p, __ATOMIC_RELAXED, __HIP_MEMORY_SCOPE_AGENT); }
; __device__ __forceinline__ unsigned xb_add(unsigned* p, unsigned v) { return __hip_atomic_fetch_add(p, v, __ATOMIC_RELAXED, __HIP_MEMORY_SCOPE_AGENT); }
; __device__ __forceinline__ void xcd_local_barrier(unsigned* xl, unsigned x) {
;     asm volatile("s_waitcnt vmcnt(0)" ::: "memory");
;     __syncthreads();
;     if (threadIdx.x == 0) {
;         __builtin_amdgcn_s_waitcnt(0);
;         unsigned* sub = xl + 512 + 64 * x; unsigned* gen = xl + 1024 + 64 * x;
;         const unsigned old = xb_add(sub, 1u), g = old / 32u;
;         if (old + 1u == (g + 1u) * 32u) (void)xb_add(gen, 1u);
;         else { unsigned sp = 0; while (xb_ld(gen) == g) { __builtin_amdgcn_s_sleep(1); if (++sp > (1u << 22)) break; } }
;         __builtin_amdgcn_fence(__ATOMIC_ACQUIRE, "agent");
;         asm volatile("s_waitcnt vmcnt(0)" ::: "memory");
;     }
;     __syncthreads();
.LBB0_1534:
	s_and_b64 vcc, exec, s[2:3]
	s_cbranch_vccz .LBB0_1558
	s_waitcnt vmcnt(0)
	s_waitcnt lgkmcnt(0)
	s_barrier
	s_and_saveexec_b64 s[2:3], s[90:91]
	s_cbranch_execz .LBB0_1557
	s_lshl_b32 s4, s92, 8
	s_add_u32 s4, s74, s4
	s_addc_u32 s5, s75, 0
	v_mov_b32_e32 v0, 0xd000
	v_mov_b32_e32 v1, 1
	s_waitcnt vmcnt(0) lgkmcnt(0)
	global_atomic_add v0, v1, s[4:5]
	s_mov_b32 s23, 0x40000
.Lxs5_spin:
	global_load_dword v2, v0, s[4:5] sc1
	s_waitcnt vmcnt(0)
	v_cmp_gt_u32_e32 vcc, 0xe0, v2
	s_cbranch_vccz .Lxs5_done
	s_sleep 1
	s_sub_u32 s23, s23, 1
	s_cmp_lg_u32 s23, 0
	s_cbranch_scc1 .Lxs5_spin
.Lxs5_done:
	buffer_inv sc1
	s_waitcnt vmcnt(0)
.LBB0_1557:
	s_or_b64 exec, exec, s[2:3]
	s_barrier

; __device__ __forceinline__ unsigned xb_ld(unsigned* p)              { return __hip_atomic_load(p, __ATOMIC_RELAXED, __HIP_MEMORY_SCOPE_AGENT); }
; __device__ __forceinline__ unsigned xb_add(unsigned* p, unsigned v) { return __hip_atomic_fetch_add(p, v, __ATOMIC_RELAXED, __HIP_MEMORY_SCOPE_AGENT); }
; __device__ __forceinline__ void xcd_local_barrier(unsigned* xl, unsigned x) {
;     asm volatile("s_waitcnt vmcnt(0)" ::: "memory");
;     __syncthreads();
;     if (threadIdx.x == 0) {
;         __builtin_amdgcn_s_waitcnt(0);
;         unsigned* sub = xl + 512 + 64 * x; unsigned* gen = xl + 1024 + 64 * x;
;         const unsigned old = xb_add(sub, 1u), g = old / 32u;
;         if (old + 1u == (g + 1u) * 32u) (void)xb_add(gen, 1u);
;         else { unsigned sp = 0; while (xb_ld(gen) == g) { __builtin_amdgcn_s_sleep(1); if (++sp > (1u << 22)) break; } }
;         __builtin_amdgcn_fence(__ATOMIC_ACQUIRE, "agent");
;         asm volatile("s_waitcnt vmcnt(0)" ::: "memory");
;     }
;     __syncthreads();
.LBB0_1674:
	s_and_b64 vcc, exec, s[2:3]
	s_cbranch_vccz .LBB0_1698
	s_waitcnt vmcnt(0)
	s_waitcnt vmcnt(0) lgkmcnt(0)
	s_barrier
	s_and_saveexec_b64 s[2:3], s[90:91]
	s_cbranch_execz .LBB0_1697
	s_lshl_b32 s0, s92, 8
	s_add_u32 s0, s74, s0
	s_addc_u32 s1, s75, 0
	v_mov_b32_e32 v0, 0xd000
	v_mov_b32_e32 v1, 1
	s_waitcnt vmcnt(0) lgkmcnt(0)
	global_atomic_add v0, v1, s[0:1]
	s_mov_b32 s22, 0x40000
.Lxs6_spin:
	global_load_dword v2, v0, s[0:1] sc1
	s_waitcnt vmcnt(0)
	v_cmp_gt_u32_e32 vcc, 0x100, v2
	s_cbranch_vccz .Lxs6_done
	s_sleep 1
	s_sub_u32 s22, s22, 1
	s_cmp_lg_u32 s22, 0
	s_cbranch_scc1 .Lxs6_spin
.Lxs6_done:
	buffer_inv sc1
	s_waitcnt vmcnt(0)
.LBB0_1697:
	s_or_b64 exec, exec, s[2:3]
	s_barrier
